# scan: kd-transpose LDS image slot swizzle, state-update fragment reads bank-conflict free
# speedup vs baseline: 1.0029x; 1.0029x over previous
; __device__ __forceinline__ int opaque_tid() { int t = threadIdx.x; asm volatile("" : "+v"(t)); return t; }
; __device__ __forceinline__ void scan_phase(LAS unsigned char* lds, bf16* proj, int G, int bid) {
;     const int tid = opaque_tid(), lane = tid & 63, wave = tid >> 6, fr = lane & 15, fq = lane >> 4;
;     constexpr int KRS = 132;
;     constexpr int SET = 34304, O_KR = 0, O_QR = 8448, O_QE = 16896, O_KE = 21248, O_KD = 25600, O_DV = 33792, O_VT = 2 * SET, QST = 272;
;     const int st = tid >> 4, sc8 = tid & 15;
;     const int pdk = tid >> 2, ptq = tid & 3;
;     const bool stager = tid < 256;
;     ...
;     for (int chain = bid; chain < 256; chain += G) {
;         const int b = chain >> 4, h = (chain >> 1) & 7, dir = chain & 1;
;         const int kcol = 1024 + dir * 1024 + h * 128;
;         f32x4 S[8];
; #pragma unroll
;         for (int i = 0; i < 8; ++i) S[i] = (f32x4){0.f, 0.f, 0.f, 0.f};
;         u32x4 rk = (u32x4){0u, 0u, 0u, 0u}, rq = rk, rv = rk;
.LBB0_413:
	s_or_b64 exec, exec, s[0:1]
	v_readlane_b32 s0, v255, 33
	v_readlane_b32 s1, v255, 34
	s_xor_b64 s[0:1], s[0:1], -1
	v_writelane_b32 v255, s0, 46
	s_waitcnt lgkmcnt(0)
	s_barrier
	v_writelane_b32 v255, s1, 47
	s_nop 0
	v_readlane_b32 s0, v255, 39
	v_readlane_b32 s1, v255, 40
	s_and_b64 vcc, exec, s[0:1]
	s_mov_b64 s[0:1], -1
	s_cbranch_vccnz .LBB0_592
	v_readlane_b32 s4, v254, 43
	v_readlane_b32 s5, v254, 44
	s_and_b64 vcc, exec, s[4:5]
	s_cbranch_vccz .LBB0_496
	v_readlane_b32 s0, v253, 62
	v_readlane_b32 s1, v253, 63
	s_mov_b64 s[24:25], s[42:43]
	v_mov_b32_e32 v0, v209
	s_andn2_b64 vcc, exec, s[0:1]
	s_cbranch_vccnz .LBB0_444
	s_movk_i32 s0, 0x100
	v_ashrrev_i32_e32 v71, 2, v0
	v_cmp_gt_i32_e64 s[38:39], s0, v0
	s_movk_i32 s0, 0x200
	v_ashrrev_i32_e32 v70, 4, v0
	v_lshlrev_b32_e32 v72, 1, v71
	v_cmp_gt_i32_e64 s[42:43], s0, v0
	s_movk_i32 s0, 0x84
	v_and_b32_e32 v53, 15, v0
	v_add_u32_e32 v1, 0, v72
	s_waitcnt vmcnt(2)
	v_mul_lo_u32 v6, v70, s0
	v_add_u32_e32 v4, v1, v72
	v_bfe_u32 v5, v0, 4, 2
	v_lshlrev_b32_e32 v75, 2, v6
	v_lshlrev_b32_e32 v6, 5, v53
	s_waitcnt vmcnt(0)
	v_ashrrev_i32_e32 v8, 3, v0
	v_add3_u32 v76, 0, v75, v6
	v_lshlrev_b32_e32 v6, 9, v53
	v_readlane_b32 s4, v254, 11
	v_lshlrev_b32_e32 v8, 1, v8
	v_lshlrev_b32_e32 v9, 1, v70
	v_mad_u64_u32 v[54:55], s[0:1], v71, 60, v[4:5]
	v_and_b32_e32 v3, 3, v0
	v_add_u32_e32 v7, s4, v6
	v_and_b32_e32 v8, -16, v8
	v_and_b32_e32 v9, 6, v9
	s_movk_i32 s0, 0xffc4
	v_add3_u32 v77, v7, v8, v9
	v_mul_u32_u24_e32 v80, 0x210, v3
	v_mul_u32_u24_e32 v7, 0x220, v3
	v_mul_lo_u32 v84, v71, s0
	v_readlane_b32 s0, v254, 12
	v_lshl_add_u32 v81, v80, 2, v4
	v_lshl_add_u32 v82, v7, 1, v1
	v_add_u32_e32 v1, s0, v6
	v_and_b32_e32 v4, -16, v71
	v_add3_u32 v85, v1, v8, v9
	v_and_b32_e32 v204, 3, v53
	v_lshlrev_b32_e32 v204, 4, v204
	v_xor_b32_e32 v77, v77, v204
	v_xor_b32_e32 v85, v85, v204
	v_bfe_u32 v204, v53, 2, 1
	v_lshlrev_b32_e32 v204, 6, v204
	v_sub_u32_e32 v180, v77, v204
	v_sub_u32_e32 v181, v85, v204
	v_add_u32_e32 v77, v77, v204
	v_add_u32_e32 v85, v85, v204
	v_lshlrev_b32_e32 v89, 4, v5
	v_lshlrev_b32_e32 v56, 3, v5
	v_lshlrev_b32_e32 v1, 2, v5
	v_ashrrev_i32_e32 v5, 31, v4
	v_lshl_add_u64 v[4:5], v[4:5], 1, s[82:83]
	v_mov_b32_e32 v57, v2
	v_lshlrev_b32_e32 v83, 6, v71
	v_lshl_add_u64 v[58:59], v[4:5], 0, v[56:57]
	v_lshlrev_b32_e32 v4, 4, v53
	v_mov_b32_e32 v5, v2
	s_movk_i32 s0, 0x10ff
	v_cmp_lt_i32_e64 s[40:41], s22, v0
	v_lshlrev_b32_e32 v73, 4, v0
	v_lshl_add_u64 v[60:61], s[82:83], 0, v[4:5]
	v_lshlrev_b32_e32 v57, 6, v53
	v_cmp_gt_u32_e64 s[48:49], v1, v53
	v_cmp_lt_u32_e64 s[50:51], v1, v53
	v_or_b32_e32 v4, 2, v1
	v_or_b32_e32 v1, 3, v1
	v_bitop3_b32 v92, v0, s0, 15 bitop3:0x6c
	v_and_b32_e32 v0, 0xfffffc00, v83
	v_cmp_gt_u32_e64 s[54:55], v1, v53
	v_lshlrev_b32_e32 v1, 10, v3
	v_or3_b32 v0, v0, v57, v89
	v_sub_u32_e32 v74, 0xff, v70
	v_lshlrev_b32_e32 v52, 3, v53
	v_add_u32_e32 v78, 16, v70
	v_sub_u32_e32 v79, 0xef, v70
	v_cmp_eq_u32_e64 s[44:45], 0, v3
	v_cmp_lt_u32_e64 s[46:47], 1, v3
	v_lshlrev_b32_e32 v55, 4, v3
	v_bfe_u32 v206, v209, 4, 2
	v_sub_u32_e32 v206, 0, v206
	v_and_b32_e32 v206, 3, v206
	v_lshlrev_b32_e32 v206, 4, v206
	v_xor_b32_e32 v55, v55, v206
	v_bfe_u32 v207, v209, 2, 2
	v_sub_u32_e32 v207, 0, v207
	v_and_b32_e32 v207, 3, v207
	v_bfe_u32 v208, v209, 4, 2
	v_xor_b32_e32 v207, v207, v208
	v_sub_u32_e32 v207, v207, v208
	v_lshlrev_b32_e32 v207, 4, v207
	v_add_u32_e32 v207, v207, v57
	v_add_u32_e32 v86, 32, v70
	v_sub_u32_e32 v87, 0xdf, v70
	v_mul_u32_u24_e32 v88, 0x110, v53
	v_cmp_gt_u32_e64 s[52:53], v4, v53
	v_sub_u32_e32 v90, 0, v1
	v_sub_u32_e32 v91, 0, v70
	v_lshrrev_b32_e32 v204, 5, v0
	v_and_b32_e32 v204, 0x70, v204
	v_xor_b32_e32 v0, v0, v204
	v_add_u32_e32 v93, s4, v0
	s_mov_b32 s13, s2
	s_branch .LBB0_418

; #define LAS __attribute__((address_space(3)))
; #define SC_LOAD(c_) do { const bf16* rp_ = proj + (size_t)scan_row16(b, dir, (c_), st) * HIN + h * 128 + sc8 * 8; \
;         rq = *(const u32x4*)rp_; rk = *(const u32x4*)(rp_ + kcol - h * 128); rv = *(const u32x4*)(rp_ + 3072); } while (0)
; __device__ __forceinline__ void scan_phase(LAS unsigned char* lds, bf16* proj, int G, int bid) {
;     ...
;         __syncthreads();
;         {
;             const u32x4 z4 = (u32x4){0u, 0u, 0u, 0u};
;             for (int o_ = tid * 16; o_ < 8192; o_ += NTHR * 16) { *(LAS u32x4*)(lds + O_KD + o_) = z4; *(LAS u32x4*)(lds + SET + O_KD + o_) = z4; *(LAS u32x4*)(lds + O_VT + o_) = z4; *(LAS u32x4*)(lds + O_VT + 8192 + o_) = z4; *(LAS u32x4*)(lds + O_VT + 16384 + o_) = z4; }
;         }
;         if (stager) SC_LOAD(0);
;         __syncthreads();
;         if (stager) { SC_WRITE(0); SC_LOAD(1); }
;         __syncthreads();
;         SC_PREP(0);
;         if (stager) { SC_WRITE(1); SC_LOAD(2); }
;         __syncthreads();
; #pragma unroll 1
;         for (int c = 0; c < 272; ++c) {
;             LAS unsigned char* set = lds + (c & 1) * SET;
;             SC_PREP(c + 1);
;             {
;                 const LAS unsigned char* qeb = set + O_QE + fr * QST; const LAS unsigned char* keb = set + O_KE + fr * QST;
;                 bf16x8 kaf[4], qbf[4];
; #pragma unroll
;                 for (int i = 0; i < 4; ++i) { kaf[i] = *(const LAS bf16x8*)(keb + (32 * i + fq * 8) * 2); qbf[i] = *(const LAS bf16x8*)(qeb + (32 * i + fq * 8) * 2); }
;                 u32x2 qlo[4], qhi[4];
; #pragma unroll
;                 for (int i = 0; i < 4; ++i) { qlo[i] = *(const LAS u32x2*)(qeb + (32 * i + fq * 4) * 2); qhi[i] = *(const LAS u32x2*)(qeb + (32 * i + 16 + fq * 4) * 2); }
;                 const bf16x8 vf = *(const LAS bf16x8*)(lds + O_VT + (c % 3) * 8192 + (wave * 16 + fr) * 64 + fq * 16);
;                 f32x4 pt = (f32x4){0.f, 0.f, 0.f, 0.f};
;                 __builtin_amdgcn_s_setprio(1);
; #pragma unroll
;                 for (int i = 0; i < 4; ++i) pt = __builtin_amdgcn_mfma_f32_16x16x32_bf16(kaf[i], qbf[i], pt, 0, 0, 0);
.LBB0_433:
	s_add_i32 s7, s6, 1
	s_bitcmp1_b32 s7, 0
	s_cselect_b32 s0, 0x8600, 0
	s_add_i32 s0, s0, 0
	v_lshl_add_u32 v1, v80, 2, s0
	v_lshl_add_u32 v0, v71, 2, v1
	ds_read2_b32 v[48:49], v0 offset1:132
	v_add_u32_e32 v3, 0x2000, v0
	ds_read2_b32 v[50:51], v3 offset0:64 offset1:196
	v_add_u32_e32 v3, 0x400, v0
	ds_read2_b32 v[98:99], v3 offset0:8 offset1:140
	v_add_u32_e32 v0, 0x2400, v0
	ds_read2_b32 v[100:101], v0 offset0:72 offset1:204
	s_waitcnt lgkmcnt(3)
	v_sub_f32_e32 v0, 1.0, v48
	v_max_f32_e32 v3, 0x3bdb8bac, v0
	v_sub_f32_e32 v0, 1.0, v49
	v_max_f32_e32 v0, 0x3bdb8bac, v0
	v_mul_f32_e32 v65, v3, v0
	s_waitcnt lgkmcnt(1)
	v_sub_f32_e32 v0, 1.0, v98
	v_max_f32_e32 v0, 0x3bdb8bac, v0
	v_mul_f32_e32 v104, v65, v0
	v_sub_f32_e32 v0, 1.0, v99
	v_max_f32_e32 v0, 0x3bdb8bac, v0
	v_mul_f32_e32 v105, v104, v0
	v_add3_u32 v1, v1, v90, v72
	s_nop 0
	v_mul_f32_dpp v0, v105, v105 quad_perm:[0,0,1,2] row_mask:0xf bank_mask:0xf bound_ctrl:1
	v_cndmask_b32_e64 v0, v0, v105, s[44:45]
	s_nop 1
	v_mul_f32_dpp v102, v0, v0 quad_perm:[0,0,0,1] row_mask:0xf bank_mask:0xf bound_ctrl:1
	v_cndmask_b32_e64 v102, v0, v102, s[46:47]
	v_mov_b32_e32 v0, 0
	s_nop 1
	v_mov_b32_dpp v0, v102 quad_perm:[0,0,1,2] row_mask:0xf bank_mask:0xf
	v_cndmask_b32_e64 v106, v0, 1.0, s[44:45]
	v_mov_b32_e32 v0, 0
	v_mul_f32_e32 v3, v3, v106
	s_nop 0
	v_mov_b32_dpp v0, v102 quad_perm:[3,3,3,3] row_mask:0xf bank_mask:0xf
	v_rcp_f32_e32 v102, v3
	v_mul_f32_e32 v3, v50, v3
	v_cvt_pk_bf16_f32 v3, v3, s0
	ds_write_b16 v1, v3 offset:16896
	v_mul_f32_e32 v3, v65, v106
	v_rcp_f32_e32 v103, v3
	v_mul_f32_e32 v3, v51, v3
	v_cvt_pk_bf16_f32 v3, v3, s0
	ds_write_b16 v1, v3 offset:17168
	v_mul_f32_e32 v3, v104, v106
	v_rcp_f32_e32 v50, v3
	s_waitcnt lgkmcnt(2)
	v_mul_f32_e32 v3, v100, v3
	v_cvt_pk_bf16_f32 v3, v3, s0
	ds_write_b16 v1, v3 offset:17440
	v_mul_f32_e32 v3, v105, v106
	v_rcp_f32_e32 v51, v3
	v_mul_f32_e32 v3, v101, v3
	v_cvt_pk_bf16_f32 v3, v3, s0
	v_pk_mul_f32 v[48:49], v[48:49], v[102:103]
	ds_write_b16 v1, v3 offset:17712
	v_cvt_pk_bf16_f32 v3, v48, s0
	ds_write_b16 v1, v3 offset:21248
	v_cvt_pk_bf16_f32 v3, v49, s0
	v_pk_mul_f32 v[50:51], v[98:99], v[50:51]
	ds_write_b16 v1, v3 offset:21520
	v_cvt_pk_bf16_f32 v3, v50, s0
	ds_write_b16 v1, v3 offset:21792
	v_cvt_pk_bf16_f32 v3, v51, s0
	v_pk_mul_f32 v[100:101], v[48:49], v[0:1] op_sel_hi:[1,0]
	v_pk_mul_f32 v[98:99], v[50:51], v[0:1] op_sel_hi:[1,0]
	ds_write_b16 v1, v3 offset:22064
	v_add_u32_e32 v1, s0, v83
	v_cvt_pk_bf16_f32 v48, v100, v101
	v_cvt_pk_bf16_f32 v49, v98, v99
	v_add_u32_e32 v3, v1, v55
	ds_write_b64 v3, v[48:49] offset:25600
	s_and_saveexec_b64 s[0:1], s[44:45]
	v_add_u32_e32 v1, v1, v84
	ds_write_b32 v1, v0 offset:33792
	s_or_b64 exec, exec, s[0:1]
	s_mul_hi_u32 s0, s6, 0xaaaaaaab
	s_lshr_b32 s0, s0, 1
	s_bitcmp1_b32 s6, 0
	s_cselect_b32 s1, 0x8600, 0
	s_add_i32 s14, s1, 0
	v_add_u32_e32 v0, s14, v88
	v_add_u32_e32 v1, v0, v89
	ds_read_b128 v[48:51], v1 offset:21248
	ds_read_b128 v[98:101], v1 offset:21312
	ds_read_b128 v[102:105], v1 offset:16896
	ds_read_b128 v[106:109], v1 offset:16960
	ds_read_b128 v[110:113], v1 offset:21376
	ds_read_b128 v[114:117], v1 offset:21440
	ds_read_b128 v[118:121], v1 offset:17024
	ds_read_b128 v[122:125], v1 offset:17088
	v_add_u32_e32 v0, v0, v56
	v_add_u32_e32 v0, 0x4000, v0
	ds_read2_b64 v[126:129], v0 offset0:64 offset1:68
	ds_read2_b64 v[130:133], v0 offset0:72 offset1:76
	ds_read2_b64 v[134:137], v0 offset0:80 offset1:84
	ds_read2_b64 v[138:141], v0 offset0:88 offset1:92
	s_mulk_i32 s0, 0xa000
	v_add_u32_e32 v0, s0, v95
	ds_read_b128 v[142:145], v0
	s_setprio 1
	s_waitcnt lgkmcnt(10)
	v_mfma_f32_16x16x32_bf16 v[48:51], v[48:51], v[102:105], 0
	v_add_u32_e32 v0, s14, v89
	v_add_u32_e32 v1, v0, v207
	v_cvt_pk_bf16_f32 v146, v44, v45
	s_waitcnt lgkmcnt(9)
; #define LAS __attribute__((address_space(3)))
; __device__ __forceinline__ void scan_phase(LAS unsigned char* lds, bf16* proj, int G, int bid) {
;     ...
;                 for (int i = 0; i < 4; ++i) pt = __builtin_amdgcn_mfma_f32_16x16x32_bf16(kaf[i], qbf[i], pt, 0, 0, 0);
;                 f32x4 oacc = (f32x4){0.f, 0.f, 0.f, 0.f};
; #pragma unroll
;                 for (int i = 0; i < 4; ++i) {
;                     u32x4 sw; sw.x = cvt_pk_bf16(S[2 * i][0], S[2 * i][1]); sw.y = cvt_pk_bf16(S[2 * i][2], S[2 * i][3]); sw.z = cvt_pk_bf16(S[2 * i + 1][0], S[2 * i + 1][1]); sw.w = cvt_pk_bf16(S[2 * i + 1][2], S[2 * i + 1][3]);
;                     u32x4 qw; qw.x = qlo[i][0]; qw.y = qlo[i][1]; qw.z = qhi[i][0]; qw.w = qhi[i][1];
;                     oacc = __builtin_amdgcn_mfma_f32_16x16x32_bf16(__builtin_bit_cast(bf16x8, sw), __builtin_bit_cast(bf16x8, qw), oacc, 0, 0, 0);
;                 }
;                 const LAS float* dv = (const LAS float*)(set + O_DV);
; #pragma unroll
;                 for (int kt = 0; kt < 8; ++kt) {
;                     const f32x4 d4 = *(const LAS f32x4*)(dv + kt * 16 + fq * 4);
;                     const bf16x8 ka = *(const LAS bf16x8*)(set + O_KD + (kt * 16 + fr) * 64 + fq * 16);
;                     S[kt] = __builtin_amdgcn_mfma_f32_16x16x32_bf16(ka, vf, S[kt] * d4, 0, 0, 0);
;                 }
; #pragma unroll
;                 for (int j = 0; j < 4; ++j) pt[j] = (fq * 4 + j <= fr) ? pt[j] : 0.f;
;                 u32x4 pw; pw.x = cvt_pk_bf16(pt[0], pt[1]); pw.y = cvt_pk_bf16(pt[2], pt[3]); pw.z = 0u; pw.w = 0u;
;                 oacc = __builtin_amdgcn_mfma_f32_16x16x32_bf16(vf, __builtin_bit_cast(bf16x8, pw), oacc, 0, 0, 0);
;                 __builtin_amdgcn_s_setprio(0);
	v_mfma_f32_16x16x32_bf16 v[48:51], v[98:101], v[106:109], v[48:51]
	ds_read_b128 v[98:101], v1 offset:25600
	ds_read_b128 v[104:107], v0 offset:33792
	v_cvt_pk_bf16_f32 v147, v46, v47
	v_cvt_pk_bf16_f32 v148, v16, v17
	s_waitcnt lgkmcnt(8)
	v_mfma_f32_16x16x32_bf16 v[48:51], v[110:113], v[118:121], v[48:51]
	ds_read_b128 v[108:111], v0 offset:33856
	ds_read_b128 v[118:121], v1 offset:26624
	s_waitcnt lgkmcnt(2)
	v_pk_mul_f32 v[46:47], v[46:47], v[106:107]
	v_pk_mul_f32 v[44:45], v[44:45], v[104:105]
	ds_read_b128 v[158:161], v1 offset:32768
	s_waitcnt lgkmcnt(2)
	v_pk_mul_f32 v[16:17], v[16:17], v[108:109]
	v_mfma_f32_16x16x32_bf16 v[44:47], v[98:101], v[142:145], v[44:47]
	ds_read_b128 v[98:101], v1 offset:27648
	ds_read_b128 v[106:109], v0 offset:33920
	v_cvt_pk_bf16_f32 v149, v18, v19
	v_cvt_pk_bf16_f32 v150, v20, v21
	v_cvt_pk_bf16_f32 v151, v22, v23
	v_pk_mul_f32 v[18:19], v[18:19], v[110:111]
	s_waitcnt lgkmcnt(0)
	v_pk_mul_f32 v[22:23], v[22:23], v[108:109]
	v_pk_mul_f32 v[20:21], v[20:21], v[106:107]
	v_mfma_f32_16x16x32_bf16 v[16:19], v[118:121], v[142:145], v[16:19]
	ds_read_b128 v[110:113], v0 offset:33984
	ds_read_b128 v[118:121], v1 offset:28672
	v_cvt_pk_bf16_f32 v152, v24, v25
	v_cvt_pk_bf16_f32 v153, v26, v27
	v_mfma_f32_16x16x32_bf16 v[20:23], v[98:101], v[142:145], v[20:23]
	ds_read_b128 v[98:101], v1 offset:29696
	ds_read_b128 v[106:109], v0 offset:34048
	s_waitcnt lgkmcnt(3)
	v_pk_mul_f32 v[26:27], v[26:27], v[112:113]
	v_pk_mul_f32 v[24:25], v[24:25], v[110:111]
	v_cvt_pk_bf16_f32 v154, v28, v29
	v_cvt_pk_bf16_f32 v155, v30, v31
	s_waitcnt lgkmcnt(2)
	v_mfma_f32_16x16x32_bf16 v[24:27], v[118:121], v[142:145], v[24:27]
	ds_read_b128 v[110:113], v1 offset:30720
	ds_read_b128 v[118:121], v0 offset:34112
	s_waitcnt lgkmcnt(2)
	v_pk_mul_f32 v[30:31], v[30:31], v[108:109]
	v_pk_mul_f32 v[28:29], v[28:29], v[106:107]
	v_cvt_pk_bf16_f32 v156, v32, v33
	v_cvt_pk_bf16_f32 v157, v34, v35
	v_mfma_f32_16x16x32_bf16 v[28:31], v[98:101], v[142:145], v[28:31]
	ds_read_b128 v[98:101], v0 offset:34176
	s_waitcnt lgkmcnt(1)
	v_pk_mul_f32 v[34:35], v[34:35], v[120:121]
	v_pk_mul_f32 v[32:33], v[32:33], v[118:119]
	v_cvt_pk_bf16_f32 v102, v36, v37
	v_cvt_pk_bf16_f32 v103, v38, v39
	v_mfma_f32_16x16x32_bf16 v[32:35], v[110:113], v[142:145], v[32:35]
	ds_read_b128 v[110:113], v0 offset:34240
	s_waitcnt lgkmcnt(1)
	v_pk_mul_f32 v[38:39], v[38:39], v[100:101]
	v_pk_mul_f32 v[36:37], v[36:37], v[98:99]
	v_mfma_f32_16x16x32_bf16 v[98:101], v[146:149], v[126:129], 0
	v_cvt_pk_bf16_f32 v104, v40, v41
	ds_read_b128 v[106:109], v1 offset:31744
	v_cvt_pk_bf16_f32 v105, v42, v43
	v_mfma_f32_16x16x32_bf16 v[98:101], v[150:153], v[130:133], v[98:101]
	s_waitcnt lgkmcnt(1)
	v_pk_mul_f32 v[42:43], v[42:43], v[112:113]
	v_pk_mul_f32 v[40:41], v[40:41], v[110:111]
	v_mfma_f32_16x16x32_bf16 v[48:51], v[114:117], v[122:125], v[48:51]
	v_mfma_f32_16x16x32_bf16 v[98:101], v[154:157], v[134:137], v[98:101]
	v_mfma_f32_16x16x32_bf16 v[98:101], v[102:105], v[138:141], v[98:101]
	s_nop 5
	v_cvt_pk_bf16_f32 v0, v48, s0
	v_cvt_pk_bf16_f32 v1, v49, s0
	v_cndmask_b32_e64 v0, v0, 0, s[48:49]
	v_cndmask_b32_e64 v1, 0, v1, s[50:51]
	v_perm_b32 v0, v1, v0, s11
	v_cvt_pk_bf16_f32 v1, v50, s0
	v_cvt_pk_bf16_f32 v3, v51, s0
	v_cndmask_b32_e64 v1, v1, 0, s[52:53]
	v_cndmask_b32_e64 v3, v3, 0, s[54:55]
	v_perm_b32 v1, v3, v1, s11
	v_mov_b32_e32 v3, v2
	s_waitcnt lgkmcnt(0)
	v_mfma_f32_16x16x32_bf16 v[36:39], v[106:109], v[142:145], v[36:39]
	v_mfma_f32_16x16x32_bf16 v[40:43], v[158:161], v[142:145], v[40:43]
	v_mfma_f32_16x16x32_bf16 v[48:51], v[142:145], v[0:3], v[98:101]
	s_setprio 0
	s_mov_b64 s[0:1], -1
	s_cmp_gt_u32 s6, 15
	v_add_u32_e32 v1, s4, v53
	s_cbranch_scc0 .LBB0_437
	v_add_u32_e32 v0, 0xffffff00, v1
	v_cndmask_b32_e64 v0, v96, v0, s[56:57]
	v_add_u32_e32 v0, s5, v0
	s_mov_b64 s[0:1], 0
